# adds hand-written GATE epilogue (sigmoid as rcp(1+exp2(acc*(-log2e*rstd))), fewer VALU ops) on top of the SwiGLU/RES/MERGE/STORE epilogues and x-conversion loop
# speedup vs baseline: 1.0042x; 1.0027x over previous
; #define GAS __attribute__((address_space(1)))
; __device__ __forceinline__ u32x4 pack8(f32x4 a, f32x4 b) { u32x4 w; w.x = cvtpk(a[0], a[1]); w.y = cvtpk(a[2], a[3]); w.z = cvtpk(b[0], b[1]); w.w = cvtpk(b[2], b[3]); return w; }
; __device__ __forceinline__ f32x4 sig4(f32x4 x) { f32x4 r; r[0] = fsigmoid(x[0]); r[1] = fsigmoid(x[1]); r[2] = fsigmoid(x[2]); r[3] = fsigmoid(x[3]); return r; }
;     __device__ __forceinline__ void operator()(const f32x4 (&acc)[2][2][4][2], const Unit& u, int wr, int wc, int fr, int fq) const {
;     ...
;         } else if (mode == EM_GATE) {
;             float rsg[2][4];
; #pragma unroll
;             for (int ai = 0; ai < 2; ++ai)
; #pragma unroll
;                 for (int m = 0; m < 4; ++m) rsg[ai][m] = ssq_in[rowb + ai * HALF + m * 16];
; #pragma unroll
;             for (int ai = 0; ai < 2; ++ai)
; #pragma unroll
;                 for (int m = 0; m < 4; ++m) {
;                     const int row = rowb + ai * HALF + m * 16;
;                     const float rstd = __builtin_amdgcn_rsqf(rsg[ai][m] * (1.0f / DM) + EPS);
; #pragma unroll
;                     for (int bj = 0; bj < 2; ++bj) {
;                         const size_t off = (size_t)row * DM + u.pn * BM + bj * HALF + wc * 32 + fq * 8;
;                         *(GAS u32x4*)(o16 + off) = pack8(sig4(acc[ai][bj][m][0] * rstd), sig4(acc[ai][bj][m][1] * rstd));
;                     }
;                 }
.LBB0_193:
	s_andn2_b64 vcc, exec, s[0:1]
	s_cbranch_vccnz .LBB0_196
	s_cmp_eq_u32 s35, 3
	s_mov_b64 s[40:41], -1
	s_cbranch_scc0 .LBB0_196
	s_branch .Lgate_fast

; #define GAS __attribute__((address_space(1)))
; __device__ __forceinline__ u32x4 pack8(f32x4 a, f32x4 b) { u32x4 w; w.x = cvtpk(a[0], a[1]); w.y = cvtpk(a[2], a[3]); w.z = cvtpk(b[0], b[1]); w.w = cvtpk(b[2], b[3]); return w; }
; __device__ __forceinline__ f32x4 sig4(f32x4 x) { f32x4 r; r[0] = fsigmoid(x[0]); r[1] = fsigmoid(x[1]); r[2] = fsigmoid(x[2]); r[3] = fsigmoid(x[3]); return r; }
;     __device__ __forceinline__ void operator()(const f32x4 (&acc)[2][2][4][2], const Unit& u, int wr, int wc, int fr, int fq) const {
;     ...
;             float rsg[2][4];
; #pragma unroll
;             for (int ai = 0; ai < 2; ++ai)
; #pragma unroll
;                 for (int m = 0; m < 4; ++m) rsg[ai][m] = ssq_in[rowb + ai * HALF + m * 16];
; #pragma unroll
;             for (int ai = 0; ai < 2; ++ai)
; #pragma unroll
;                 for (int m = 0; m < 4; ++m) {
;                     const int row = rowb + ai * HALF + m * 16;
;                     const float rstd = __builtin_amdgcn_rsqf(rsg[ai][m] * (1.0f / DM) + EPS);
; #pragma unroll
;                     for (int bj = 0; bj < 2; ++bj) {
;                         const size_t off = (size_t)row * DM + u.pn * BM + bj * HALF + wc * 32 + fq * 8;
;                         *(GAS u32x4*)(o16 + off) = pack8(sig4(acc[ai][bj][m][0] * rstd), sig4(acc[ai][bj][m][1] * rstd));
;                     }
.Lgate_fast:
	s_waitcnt lgkmcnt(0)
	v_lshlrev_b32_e32 v188, 2, v182
	global_load_dword v142, v188, s[12:13]
	global_load_dword v143, v188, s[12:13] offset:64
	global_load_dword v144, v188, s[12:13] offset:128
	global_load_dword v145, v188, s[12:13] offset:192
	global_load_dword v146, v188, s[12:13] offset:512
	global_load_dword v147, v188, s[12:13] offset:576
	global_load_dword v148, v188, s[12:13] offset:640
	global_load_dword v149, v188, s[12:13] offset:704
	s_lshl_b32 s0, s67, 9
	v_lshlrev_b32_e32 v156, 11, v182
	v_lshl_add_u32 v156, v176, 1, v156
	v_add_u32_e32 v156, s0, v156
	v_mov_b32_e32 v154, 1.0
	v_mov_b32_e32 v155, 1.0
	s_waitcnt vmcnt(7)
	v_fmamk_f32 v189, v142, 0x3a800000, v210
	v_rsq_f32_e32 v189, v189
	v_mov_b32_e32 v157, v156
	v_mul_f32_e32 v150, 0xbfb8aa3b, v189
	v_pk_mul_f32 v[114:115], v[114:115], v[150:151] op_sel_hi:[1,0]
	v_pk_mul_f32 v[116:117], v[116:117], v[150:151] op_sel_hi:[1,0]
	v_pk_mul_f32 v[126:127], v[126:127], v[150:151] op_sel_hi:[1,0]
	v_pk_mul_f32 v[128:129], v[128:129], v[150:151] op_sel_hi:[1,0]
	v_exp_f32_e32 v114, v114
	v_exp_f32_e32 v115, v115
	v_exp_f32_e32 v116, v116
	v_exp_f32_e32 v117, v117
	v_exp_f32_e32 v126, v126
	v_exp_f32_e32 v127, v127
	v_exp_f32_e32 v128, v128
	v_exp_f32_e32 v129, v129
	v_pk_add_f32 v[114:115], v[114:115], v[154:155]
	v_pk_add_f32 v[116:117], v[116:117], v[154:155]
	v_pk_add_f32 v[126:127], v[126:127], v[154:155]
	v_pk_add_f32 v[128:129], v[128:129], v[154:155]
	v_rcp_f32_e32 v114, v114
	v_rcp_f32_e32 v115, v115
	v_rcp_f32_e32 v116, v116
	v_rcp_f32_e32 v117, v117
	v_rcp_f32_e32 v126, v126
	v_rcp_f32_e32 v127, v127
	v_rcp_f32_e32 v128, v128
	v_rcp_f32_e32 v129, v129
	v_cvt_pk_bf16_f32 v130, v114, v115
	v_cvt_pk_bf16_f32 v131, v116, v117
	v_cvt_pk_bf16_f32 v132, v126, v127
	v_cvt_pk_bf16_f32 v133, v128, v129
	global_store_dwordx4 v157, v[130:133], s[18:19]
	v_pk_mul_f32 v[122:123], v[122:123], v[150:151] op_sel_hi:[1,0]
	v_pk_mul_f32 v[124:125], v[124:125], v[150:151] op_sel_hi:[1,0]
	v_pk_mul_f32 v[118:119], v[118:119], v[150:151] op_sel_hi:[1,0]
	v_pk_mul_f32 v[120:121], v[120:121], v[150:151] op_sel_hi:[1,0]
	v_exp_f32_e32 v122, v122
	v_exp_f32_e32 v123, v123
	v_exp_f32_e32 v124, v124
	v_exp_f32_e32 v125, v125
	v_exp_f32_e32 v118, v118
	v_exp_f32_e32 v119, v119
	v_exp_f32_e32 v120, v120
	v_exp_f32_e32 v121, v121
	v_pk_add_f32 v[122:123], v[122:123], v[154:155]
	v_pk_add_f32 v[124:125], v[124:125], v[154:155]
	v_pk_add_f32 v[118:119], v[118:119], v[154:155]
	v_pk_add_f32 v[120:121], v[120:121], v[154:155]
	v_rcp_f32_e32 v122, v122
	v_rcp_f32_e32 v123, v123
	v_rcp_f32_e32 v124, v124
	v_rcp_f32_e32 v125, v125
	v_rcp_f32_e32 v118, v118
	v_rcp_f32_e32 v119, v119
	v_rcp_f32_e32 v120, v120
	v_rcp_f32_e32 v121, v121
	v_cvt_pk_bf16_f32 v134, v122, v123
	v_cvt_pk_bf16_f32 v135, v124, v125
	v_cvt_pk_bf16_f32 v136, v118, v119
	v_cvt_pk_bf16_f32 v137, v120, v121
	global_store_dwordx4 v157, v[134:137], s[18:19] offset:256
	s_waitcnt vmcnt(8)
	v_fmamk_f32 v189, v143, 0x3a800000, v210
	v_rsq_f32_e32 v189, v189
	v_add_u32_e32 v157, 0x8000, v156
	v_mul_f32_e32 v150, 0xbfb8aa3b, v189
	v_pk_mul_f32 v[110:111], v[110:111], v[150:151] op_sel_hi:[1,0]
	v_pk_mul_f32 v[112:113], v[112:113], v[150:151] op_sel_hi:[1,0]
	v_pk_mul_f32 v[102:103], v[102:103], v[150:151] op_sel_hi:[1,0]
	v_pk_mul_f32 v[104:105], v[104:105], v[150:151] op_sel_hi:[1,0]
	v_exp_f32_e32 v110, v110
	v_exp_f32_e32 v111, v111
	v_exp_f32_e32 v112, v112
	v_exp_f32_e32 v113, v113
	v_exp_f32_e32 v102, v102
	v_exp_f32_e32 v103, v103
	v_exp_f32_e32 v104, v104
	v_exp_f32_e32 v105, v105
	v_pk_add_f32 v[110:111], v[110:111], v[154:155]
	v_pk_add_f32 v[112:113], v[112:113], v[154:155]
	v_pk_add_f32 v[102:103], v[102:103], v[154:155]
	v_pk_add_f32 v[104:105], v[104:105], v[154:155]
	v_rcp_f32_e32 v110, v110
	v_rcp_f32_e32 v111, v111
	v_rcp_f32_e32 v112, v112
	v_rcp_f32_e32 v113, v113
	v_rcp_f32_e32 v102, v102
	v_rcp_f32_e32 v103, v103
	v_rcp_f32_e32 v104, v104
	v_rcp_f32_e32 v105, v105
	v_cvt_pk_bf16_f32 v130, v110, v111
	v_cvt_pk_bf16_f32 v131, v112, v113
	v_cvt_pk_bf16_f32 v132, v102, v103
	v_cvt_pk_bf16_f32 v133, v104, v105
	global_store_dwordx4 v157, v[130:133], s[18:19]
	v_pk_mul_f32 v[106:107], v[106:107], v[150:151] op_sel_hi:[1,0]
	v_pk_mul_f32 v[108:109], v[108:109], v[150:151] op_sel_hi:[1,0]
	v_pk_mul_f32 v[98:99], v[98:99], v[150:151] op_sel_hi:[1,0]
	v_pk_mul_f32 v[100:101], v[100:101], v[150:151] op_sel_hi:[1,0]
	v_exp_f32_e32 v106, v106
	v_exp_f32_e32 v107, v107
	v_exp_f32_e32 v108, v108
	v_exp_f32_e32 v109, v109
	v_exp_f32_e32 v98, v98
	v_exp_f32_e32 v99, v99
	v_exp_f32_e32 v100, v100
	v_exp_f32_e32 v101, v101
	v_pk_add_f32 v[106:107], v[106:107], v[154:155]
	v_pk_add_f32 v[108:109], v[108:109], v[154:155]
	v_pk_add_f32 v[98:99], v[98:99], v[154:155]
	v_pk_add_f32 v[100:101], v[100:101], v[154:155]
	v_rcp_f32_e32 v106, v106
	v_rcp_f32_e32 v107, v107
	v_rcp_f32_e32 v108, v108
	v_rcp_f32_e32 v109, v109
	v_rcp_f32_e32 v98, v98
	v_rcp_f32_e32 v99, v99
	v_rcp_f32_e32 v100, v100
	v_rcp_f32_e32 v101, v101
	v_cvt_pk_bf16_f32 v134, v106, v107
	v_cvt_pk_bf16_f32 v135, v108, v109
	v_cvt_pk_bf16_f32 v136, v98, v99
	v_cvt_pk_bf16_f32 v137, v100, v101
	global_store_dwordx4 v157, v[134:137], s[18:19] offset:256
	s_waitcnt vmcnt(9)
; #define GAS __attribute__((address_space(1)))
; __device__ __forceinline__ u32x4 pack8(f32x4 a, f32x4 b) { u32x4 w; w.x = cvtpk(a[0], a[1]); w.y = cvtpk(a[2], a[3]); w.z = cvtpk(b[0], b[1]); w.w = cvtpk(b[2], b[3]); return w; }
; __device__ __forceinline__ f32x4 sig4(f32x4 x) { f32x4 r; r[0] = fsigmoid(x[0]); r[1] = fsigmoid(x[1]); r[2] = fsigmoid(x[2]); r[3] = fsigmoid(x[3]); return r; }
;     __device__ __forceinline__ void operator()(const f32x4 (&acc)[2][2][4][2], const Unit& u, int wr, int wc, int fr, int fq) const {
;     ...
;             float rsg[2][4];
; #pragma unroll
;             for (int ai = 0; ai < 2; ++ai)
; #pragma unroll
;                 for (int m = 0; m < 4; ++m) rsg[ai][m] = ssq_in[rowb + ai * HALF + m * 16];
; #pragma unroll
;             for (int ai = 0; ai < 2; ++ai)
; #pragma unroll
;                 for (int m = 0; m < 4; ++m) {
;                     const int row = rowb + ai * HALF + m * 16;
;                     const float rstd = __builtin_amdgcn_rsqf(rsg[ai][m] * (1.0f / DM) + EPS);
; #pragma unroll
;                     for (int bj = 0; bj < 2; ++bj) {
;                         const size_t off = (size_t)row * DM + u.pn * BM + bj * HALF + wc * 32 + fq * 8;
;                         *(GAS u32x4*)(o16 + off) = pack8(sig4(acc[ai][bj][m][0] * rstd), sig4(acc[ai][bj][m][1] * rstd));
;                     }
	v_fmamk_f32 v189, v144, 0x3a800000, v210
	v_rsq_f32_e32 v189, v189
	v_add_u32_e32 v157, 0x10000, v156
	v_mul_f32_e32 v150, 0xbfb8aa3b, v189
	v_pk_mul_f32 v[94:95], v[94:95], v[150:151] op_sel_hi:[1,0]
	v_pk_mul_f32 v[96:97], v[96:97], v[150:151] op_sel_hi:[1,0]
	v_pk_mul_f32 v[86:87], v[86:87], v[150:151] op_sel_hi:[1,0]
	v_pk_mul_f32 v[88:89], v[88:89], v[150:151] op_sel_hi:[1,0]
	v_exp_f32_e32 v94, v94
	v_exp_f32_e32 v95, v95
	v_exp_f32_e32 v96, v96
	v_exp_f32_e32 v97, v97
	v_exp_f32_e32 v86, v86
	v_exp_f32_e32 v87, v87
	v_exp_f32_e32 v88, v88
	v_exp_f32_e32 v89, v89
	v_pk_add_f32 v[94:95], v[94:95], v[154:155]
	v_pk_add_f32 v[96:97], v[96:97], v[154:155]
	v_pk_add_f32 v[86:87], v[86:87], v[154:155]
	v_pk_add_f32 v[88:89], v[88:89], v[154:155]
	v_rcp_f32_e32 v94, v94
	v_rcp_f32_e32 v95, v95
	v_rcp_f32_e32 v96, v96
	v_rcp_f32_e32 v97, v97
	v_rcp_f32_e32 v86, v86
	v_rcp_f32_e32 v87, v87
	v_rcp_f32_e32 v88, v88
	v_rcp_f32_e32 v89, v89
	v_cvt_pk_bf16_f32 v130, v94, v95
	v_cvt_pk_bf16_f32 v131, v96, v97
	v_cvt_pk_bf16_f32 v132, v86, v87
	v_cvt_pk_bf16_f32 v133, v88, v89
	global_store_dwordx4 v157, v[130:133], s[18:19]
	v_pk_mul_f32 v[90:91], v[90:91], v[150:151] op_sel_hi:[1,0]
	v_pk_mul_f32 v[92:93], v[92:93], v[150:151] op_sel_hi:[1,0]
	v_pk_mul_f32 v[82:83], v[82:83], v[150:151] op_sel_hi:[1,0]
	v_pk_mul_f32 v[84:85], v[84:85], v[150:151] op_sel_hi:[1,0]
	v_exp_f32_e32 v90, v90
	v_exp_f32_e32 v91, v91
	v_exp_f32_e32 v92, v92
	v_exp_f32_e32 v93, v93
	v_exp_f32_e32 v82, v82
	v_exp_f32_e32 v83, v83
	v_exp_f32_e32 v84, v84
	v_exp_f32_e32 v85, v85
	v_pk_add_f32 v[90:91], v[90:91], v[154:155]
	v_pk_add_f32 v[92:93], v[92:93], v[154:155]
	v_pk_add_f32 v[82:83], v[82:83], v[154:155]
	v_pk_add_f32 v[84:85], v[84:85], v[154:155]
	v_rcp_f32_e32 v90, v90
	v_rcp_f32_e32 v91, v91
	v_rcp_f32_e32 v92, v92
	v_rcp_f32_e32 v93, v93
	v_rcp_f32_e32 v82, v82
	v_rcp_f32_e32 v83, v83
	v_rcp_f32_e32 v84, v84
	v_rcp_f32_e32 v85, v85
	v_cvt_pk_bf16_f32 v134, v90, v91
	v_cvt_pk_bf16_f32 v135, v92, v93
	v_cvt_pk_bf16_f32 v136, v82, v83
	v_cvt_pk_bf16_f32 v137, v84, v85
	global_store_dwordx4 v157, v[134:137], s[18:19] offset:256
	s_waitcnt vmcnt(10)
	v_fmamk_f32 v189, v145, 0x3a800000, v210
	v_rsq_f32_e32 v189, v189
	v_add_u32_e32 v157, 0x18000, v156
	v_mul_f32_e32 v150, 0xbfb8aa3b, v189
	v_pk_mul_f32 v[78:79], v[78:79], v[150:151] op_sel_hi:[1,0]
	v_pk_mul_f32 v[80:81], v[80:81], v[150:151] op_sel_hi:[1,0]
	v_pk_mul_f32 v[70:71], v[70:71], v[150:151] op_sel_hi:[1,0]
	v_pk_mul_f32 v[72:73], v[72:73], v[150:151] op_sel_hi:[1,0]
	v_exp_f32_e32 v78, v78
	v_exp_f32_e32 v79, v79
	v_exp_f32_e32 v80, v80
	v_exp_f32_e32 v81, v81
	v_exp_f32_e32 v70, v70
	v_exp_f32_e32 v71, v71
	v_exp_f32_e32 v72, v72
	v_exp_f32_e32 v73, v73
	v_pk_add_f32 v[78:79], v[78:79], v[154:155]
	v_pk_add_f32 v[80:81], v[80:81], v[154:155]
	v_pk_add_f32 v[70:71], v[70:71], v[154:155]
	v_pk_add_f32 v[72:73], v[72:73], v[154:155]
	v_rcp_f32_e32 v78, v78
	v_rcp_f32_e32 v79, v79
	v_rcp_f32_e32 v80, v80
	v_rcp_f32_e32 v81, v81
	v_rcp_f32_e32 v70, v70
	v_rcp_f32_e32 v71, v71
	v_rcp_f32_e32 v72, v72
	v_rcp_f32_e32 v73, v73
	v_cvt_pk_bf16_f32 v130, v78, v79
	v_cvt_pk_bf16_f32 v131, v80, v81
	v_cvt_pk_bf16_f32 v132, v70, v71
	v_cvt_pk_bf16_f32 v133, v72, v73
	global_store_dwordx4 v157, v[130:133], s[18:19]
	v_pk_mul_f32 v[74:75], v[74:75], v[150:151] op_sel_hi:[1,0]
	v_pk_mul_f32 v[76:77], v[76:77], v[150:151] op_sel_hi:[1,0]
	v_pk_mul_f32 v[66:67], v[66:67], v[150:151] op_sel_hi:[1,0]
	v_pk_mul_f32 v[68:69], v[68:69], v[150:151] op_sel_hi:[1,0]
	v_exp_f32_e32 v74, v74
	v_exp_f32_e32 v75, v75
	v_exp_f32_e32 v76, v76
	v_exp_f32_e32 v77, v77
	v_exp_f32_e32 v66, v66
	v_exp_f32_e32 v67, v67
	v_exp_f32_e32 v68, v68
	v_exp_f32_e32 v69, v69
	v_pk_add_f32 v[74:75], v[74:75], v[154:155]
	v_pk_add_f32 v[76:77], v[76:77], v[154:155]
	v_pk_add_f32 v[66:67], v[66:67], v[154:155]
	v_pk_add_f32 v[68:69], v[68:69], v[154:155]
	v_rcp_f32_e32 v74, v74
	v_rcp_f32_e32 v75, v75
	v_rcp_f32_e32 v76, v76
	v_rcp_f32_e32 v77, v77
	v_rcp_f32_e32 v66, v66
	v_rcp_f32_e32 v67, v67
	v_rcp_f32_e32 v68, v68
	v_rcp_f32_e32 v69, v69
	v_cvt_pk_bf16_f32 v134, v74, v75
	v_cvt_pk_bf16_f32 v135, v76, v77
	v_cvt_pk_bf16_f32 v136, v66, v67
	v_cvt_pk_bf16_f32 v137, v68, v69
	global_store_dwordx4 v157, v[134:137], s[18:19] offset:256
	s_waitcnt vmcnt(11)
	v_fmamk_f32 v189, v146, 0x3a800000, v210
	v_rsq_f32_e32 v189, v189
	v_add_u32_e32 v157, 0x40000, v156
	v_mul_f32_e32 v150, 0xbfb8aa3b, v189
	v_pk_mul_f32 v[62:63], v[62:63], v[150:151] op_sel_hi:[1,0]
	v_pk_mul_f32 v[64:65], v[64:65], v[150:151] op_sel_hi:[1,0]
	v_pk_mul_f32 v[54:55], v[54:55], v[150:151] op_sel_hi:[1,0]
	v_pk_mul_f32 v[56:57], v[56:57], v[150:151] op_sel_hi:[1,0]
	v_exp_f32_e32 v62, v62
	v_exp_f32_e32 v63, v63
	v_exp_f32_e32 v64, v64
	v_exp_f32_e32 v65, v65
	v_exp_f32_e32 v54, v54
	v_exp_f32_e32 v55, v55
	v_exp_f32_e32 v56, v56
	v_exp_f32_e32 v57, v57
	v_pk_add_f32 v[62:63], v[62:63], v[154:155]
	v_pk_add_f32 v[64:65], v[64:65], v[154:155]
	v_pk_add_f32 v[54:55], v[54:55], v[154:155]
	v_pk_add_f32 v[56:57], v[56:57], v[154:155]
	v_rcp_f32_e32 v62, v62
	v_rcp_f32_e32 v63, v63
	v_rcp_f32_e32 v64, v64
	v_rcp_f32_e32 v65, v65
	v_rcp_f32_e32 v54, v54
	v_rcp_f32_e32 v55, v55
	v_rcp_f32_e32 v56, v56
	v_rcp_f32_e32 v57, v57
	v_cvt_pk_bf16_f32 v130, v62, v63
	v_cvt_pk_bf16_f32 v131, v64, v65
	v_cvt_pk_bf16_f32 v132, v54, v55
	v_cvt_pk_bf16_f32 v133, v56, v57
	global_store_dwordx4 v157, v[130:133], s[18:19]
	v_pk_mul_f32 v[58:59], v[58:59], v[150:151] op_sel_hi:[1,0]
	v_pk_mul_f32 v[60:61], v[60:61], v[150:151] op_sel_hi:[1,0]
	v_pk_mul_f32 v[50:51], v[50:51], v[150:151] op_sel_hi:[1,0]
	v_pk_mul_f32 v[52:53], v[52:53], v[150:151] op_sel_hi:[1,0]
	v_exp_f32_e32 v58, v58
	v_exp_f32_e32 v59, v59
	v_exp_f32_e32 v60, v60
	v_exp_f32_e32 v61, v61
	v_exp_f32_e32 v50, v50
	v_exp_f32_e32 v51, v51
	v_exp_f32_e32 v52, v52
	v_exp_f32_e32 v53, v53
	v_pk_add_f32 v[58:59], v[58:59], v[154:155]
	v_pk_add_f32 v[60:61], v[60:61], v[154:155]
	v_pk_add_f32 v[50:51], v[50:51], v[154:155]
	v_pk_add_f32 v[52:53], v[52:53], v[154:155]
	v_rcp_f32_e32 v58, v58
	v_rcp_f32_e32 v59, v59
	v_rcp_f32_e32 v60, v60
	v_rcp_f32_e32 v61, v61
	v_rcp_f32_e32 v50, v50
	v_rcp_f32_e32 v51, v51
	v_rcp_f32_e32 v52, v52
	v_rcp_f32_e32 v53, v53
	v_cvt_pk_bf16_f32 v134, v58, v59
	v_cvt_pk_bf16_f32 v135, v60, v61
	v_cvt_pk_bf16_f32 v136, v50, v51
	v_cvt_pk_bf16_f32 v137, v52, v53
	global_store_dwordx4 v157, v[134:137], s[18:19] offset:256
	s_waitcnt vmcnt(12)
; #define GAS __attribute__((address_space(1)))
; __device__ __forceinline__ u32x4 pack8(f32x4 a, f32x4 b) { u32x4 w; w.x = cvtpk(a[0], a[1]); w.y = cvtpk(a[2], a[3]); w.z = cvtpk(b[0], b[1]); w.w = cvtpk(b[2], b[3]); return w; }
; __device__ __forceinline__ f32x4 sig4(f32x4 x) { f32x4 r; r[0] = fsigmoid(x[0]); r[1] = fsigmoid(x[1]); r[2] = fsigmoid(x[2]); r[3] = fsigmoid(x[3]); return r; }
;     __device__ __forceinline__ void operator()(const f32x4 (&acc)[2][2][4][2], const Unit& u, int wr, int wc, int fr, int fq) const {
;     ...
;             float rsg[2][4];
; #pragma unroll
;             for (int ai = 0; ai < 2; ++ai)
; #pragma unroll
;                 for (int m = 0; m < 4; ++m) rsg[ai][m] = ssq_in[rowb + ai * HALF + m * 16];
; #pragma unroll
;             for (int ai = 0; ai < 2; ++ai)
; #pragma unroll
;                 for (int m = 0; m < 4; ++m) {
;                     const int row = rowb + ai * HALF + m * 16;
;                     const float rstd = __builtin_amdgcn_rsqf(rsg[ai][m] * (1.0f / DM) + EPS);
; #pragma unroll
;                     for (int bj = 0; bj < 2; ++bj) {
;                         const size_t off = (size_t)row * DM + u.pn * BM + bj * HALF + wc * 32 + fq * 8;
;                         *(GAS u32x4*)(o16 + off) = pack8(sig4(acc[ai][bj][m][0] * rstd), sig4(acc[ai][bj][m][1] * rstd));
;                     }
	v_fmamk_f32 v189, v147, 0x3a800000, v210
	v_rsq_f32_e32 v189, v189
	v_add_u32_e32 v157, 0x48000, v156
	v_mul_f32_e32 v150, 0xbfb8aa3b, v189
	v_pk_mul_f32 v[46:47], v[46:47], v[150:151] op_sel_hi:[1,0]
	v_pk_mul_f32 v[48:49], v[48:49], v[150:151] op_sel_hi:[1,0]
	v_pk_mul_f32 v[38:39], v[38:39], v[150:151] op_sel_hi:[1,0]
	v_pk_mul_f32 v[40:41], v[40:41], v[150:151] op_sel_hi:[1,0]
	v_exp_f32_e32 v46, v46
	v_exp_f32_e32 v47, v47
	v_exp_f32_e32 v48, v48
	v_exp_f32_e32 v49, v49
	v_exp_f32_e32 v38, v38
	v_exp_f32_e32 v39, v39
	v_exp_f32_e32 v40, v40
	v_exp_f32_e32 v41, v41
	v_pk_add_f32 v[46:47], v[46:47], v[154:155]
	v_pk_add_f32 v[48:49], v[48:49], v[154:155]
	v_pk_add_f32 v[38:39], v[38:39], v[154:155]
	v_pk_add_f32 v[40:41], v[40:41], v[154:155]
	v_rcp_f32_e32 v46, v46
	v_rcp_f32_e32 v47, v47
	v_rcp_f32_e32 v48, v48
	v_rcp_f32_e32 v49, v49
	v_rcp_f32_e32 v38, v38
	v_rcp_f32_e32 v39, v39
	v_rcp_f32_e32 v40, v40
	v_rcp_f32_e32 v41, v41
	v_cvt_pk_bf16_f32 v130, v46, v47
	v_cvt_pk_bf16_f32 v131, v48, v49
	v_cvt_pk_bf16_f32 v132, v38, v39
	v_cvt_pk_bf16_f32 v133, v40, v41
	global_store_dwordx4 v157, v[130:133], s[18:19]
	v_pk_mul_f32 v[42:43], v[42:43], v[150:151] op_sel_hi:[1,0]
	v_pk_mul_f32 v[44:45], v[44:45], v[150:151] op_sel_hi:[1,0]
	v_pk_mul_f32 v[34:35], v[34:35], v[150:151] op_sel_hi:[1,0]
	v_pk_mul_f32 v[36:37], v[36:37], v[150:151] op_sel_hi:[1,0]
	v_exp_f32_e32 v42, v42
	v_exp_f32_e32 v43, v43
	v_exp_f32_e32 v44, v44
	v_exp_f32_e32 v45, v45
	v_exp_f32_e32 v34, v34
	v_exp_f32_e32 v35, v35
	v_exp_f32_e32 v36, v36
	v_exp_f32_e32 v37, v37
	v_pk_add_f32 v[42:43], v[42:43], v[154:155]
	v_pk_add_f32 v[44:45], v[44:45], v[154:155]
	v_pk_add_f32 v[34:35], v[34:35], v[154:155]
	v_pk_add_f32 v[36:37], v[36:37], v[154:155]
	v_rcp_f32_e32 v42, v42
	v_rcp_f32_e32 v43, v43
	v_rcp_f32_e32 v44, v44
	v_rcp_f32_e32 v45, v45
	v_rcp_f32_e32 v34, v34
	v_rcp_f32_e32 v35, v35
	v_rcp_f32_e32 v36, v36
	v_rcp_f32_e32 v37, v37
	v_cvt_pk_bf16_f32 v134, v42, v43
	v_cvt_pk_bf16_f32 v135, v44, v45
	v_cvt_pk_bf16_f32 v136, v34, v35
	v_cvt_pk_bf16_f32 v137, v36, v37
	global_store_dwordx4 v157, v[134:137], s[18:19] offset:256
	s_waitcnt vmcnt(13)
	v_fmamk_f32 v189, v148, 0x3a800000, v210
	v_rsq_f32_e32 v189, v189
	v_add_u32_e32 v157, 0x50000, v156
	v_mul_f32_e32 v150, 0xbfb8aa3b, v189
	v_pk_mul_f32 v[30:31], v[30:31], v[150:151] op_sel_hi:[1,0]
	v_pk_mul_f32 v[32:33], v[32:33], v[150:151] op_sel_hi:[1,0]
	v_pk_mul_f32 v[22:23], v[22:23], v[150:151] op_sel_hi:[1,0]
	v_pk_mul_f32 v[24:25], v[24:25], v[150:151] op_sel_hi:[1,0]
	v_exp_f32_e32 v30, v30
	v_exp_f32_e32 v31, v31
	v_exp_f32_e32 v32, v32
	v_exp_f32_e32 v33, v33
	v_exp_f32_e32 v22, v22
	v_exp_f32_e32 v23, v23
	v_exp_f32_e32 v24, v24
	v_exp_f32_e32 v25, v25
	v_pk_add_f32 v[30:31], v[30:31], v[154:155]
	v_pk_add_f32 v[32:33], v[32:33], v[154:155]
	v_pk_add_f32 v[22:23], v[22:23], v[154:155]
	v_pk_add_f32 v[24:25], v[24:25], v[154:155]
	v_rcp_f32_e32 v30, v30
	v_rcp_f32_e32 v31, v31
	v_rcp_f32_e32 v32, v32
	v_rcp_f32_e32 v33, v33
	v_rcp_f32_e32 v22, v22
	v_rcp_f32_e32 v23, v23
	v_rcp_f32_e32 v24, v24
	v_rcp_f32_e32 v25, v25
	v_cvt_pk_bf16_f32 v130, v30, v31
	v_cvt_pk_bf16_f32 v131, v32, v33
	v_cvt_pk_bf16_f32 v132, v22, v23
	v_cvt_pk_bf16_f32 v133, v24, v25
	global_store_dwordx4 v157, v[130:133], s[18:19]
	v_pk_mul_f32 v[26:27], v[26:27], v[150:151] op_sel_hi:[1,0]
	v_pk_mul_f32 v[28:29], v[28:29], v[150:151] op_sel_hi:[1,0]
	v_pk_mul_f32 v[18:19], v[18:19], v[150:151] op_sel_hi:[1,0]
	v_pk_mul_f32 v[20:21], v[20:21], v[150:151] op_sel_hi:[1,0]
	v_exp_f32_e32 v26, v26
	v_exp_f32_e32 v27, v27
	v_exp_f32_e32 v28, v28
	v_exp_f32_e32 v29, v29
	v_exp_f32_e32 v18, v18
	v_exp_f32_e32 v19, v19
	v_exp_f32_e32 v20, v20
	v_exp_f32_e32 v21, v21
	v_pk_add_f32 v[26:27], v[26:27], v[154:155]
	v_pk_add_f32 v[28:29], v[28:29], v[154:155]
	v_pk_add_f32 v[18:19], v[18:19], v[154:155]
	v_pk_add_f32 v[20:21], v[20:21], v[154:155]
	v_rcp_f32_e32 v26, v26
	v_rcp_f32_e32 v27, v27
	v_rcp_f32_e32 v28, v28
	v_rcp_f32_e32 v29, v29
	v_rcp_f32_e32 v18, v18
	v_rcp_f32_e32 v19, v19
	v_rcp_f32_e32 v20, v20
	v_rcp_f32_e32 v21, v21
	v_cvt_pk_bf16_f32 v134, v26, v27
	v_cvt_pk_bf16_f32 v135, v28, v29
	v_cvt_pk_bf16_f32 v136, v18, v19
	v_cvt_pk_bf16_f32 v137, v20, v21
	global_store_dwordx4 v157, v[134:137], s[18:19] offset:256
	s_waitcnt vmcnt(14)
	v_fmamk_f32 v189, v149, 0x3a800000, v210
	v_rsq_f32_e32 v189, v189
	v_add_u32_e32 v157, 0x58000, v156
	v_mul_f32_e32 v150, 0xbfb8aa3b, v189
	v_pk_mul_f32 v[14:15], v[14:15], v[150:151] op_sel_hi:[1,0]
	v_pk_mul_f32 v[16:17], v[16:17], v[150:151] op_sel_hi:[1,0]
	v_pk_mul_f32 v[6:7], v[6:7], v[150:151] op_sel_hi:[1,0]
	v_pk_mul_f32 v[8:9], v[8:9], v[150:151] op_sel_hi:[1,0]
	v_exp_f32_e32 v14, v14
	v_exp_f32_e32 v15, v15
	v_exp_f32_e32 v16, v16
	v_exp_f32_e32 v17, v17
	v_exp_f32_e32 v6, v6
	v_exp_f32_e32 v7, v7
	v_exp_f32_e32 v8, v8
	v_exp_f32_e32 v9, v9
	v_pk_add_f32 v[14:15], v[14:15], v[154:155]
	v_pk_add_f32 v[16:17], v[16:17], v[154:155]
	v_pk_add_f32 v[6:7], v[6:7], v[154:155]
	v_pk_add_f32 v[8:9], v[8:9], v[154:155]
	v_rcp_f32_e32 v14, v14
	v_rcp_f32_e32 v15, v15
	v_rcp_f32_e32 v16, v16
	v_rcp_f32_e32 v17, v17
	v_rcp_f32_e32 v6, v6
	v_rcp_f32_e32 v7, v7
	v_rcp_f32_e32 v8, v8
	v_rcp_f32_e32 v9, v9
	v_cvt_pk_bf16_f32 v130, v14, v15
	v_cvt_pk_bf16_f32 v131, v16, v17
	v_cvt_pk_bf16_f32 v132, v6, v7
	v_cvt_pk_bf16_f32 v133, v8, v9
	global_store_dwordx4 v157, v[130:133], s[18:19]
	v_pk_mul_f32 v[10:11], v[10:11], v[150:151] op_sel_hi:[1,0]
	v_pk_mul_f32 v[12:13], v[12:13], v[150:151] op_sel_hi:[1,0]
	v_pk_mul_f32 v[2:3], v[2:3], v[150:151] op_sel_hi:[1,0]
	v_pk_mul_f32 v[4:5], v[4:5], v[150:151] op_sel_hi:[1,0]
	v_exp_f32_e32 v10, v10
	v_exp_f32_e32 v11, v11
	v_exp_f32_e32 v12, v12
	v_exp_f32_e32 v13, v13
	v_exp_f32_e32 v2, v2
	v_exp_f32_e32 v3, v3
	v_exp_f32_e32 v4, v4
	v_exp_f32_e32 v5, v5
	v_pk_add_f32 v[10:11], v[10:11], v[154:155]
	v_pk_add_f32 v[12:13], v[12:13], v[154:155]
	v_pk_add_f32 v[2:3], v[2:3], v[154:155]
	v_pk_add_f32 v[4:5], v[4:5], v[154:155]
	v_rcp_f32_e32 v10, v10
	v_rcp_f32_e32 v11, v11
	v_rcp_f32_e32 v12, v12
	v_rcp_f32_e32 v13, v13
	v_rcp_f32_e32 v2, v2
	v_rcp_f32_e32 v3, v3
	v_rcp_f32_e32 v4, v4
	v_rcp_f32_e32 v5, v5
	v_cvt_pk_bf16_f32 v134, v10, v11
	v_cvt_pk_bf16_f32 v135, v12, v13
	v_cvt_pk_bf16_f32 v136, v2, v3
	v_cvt_pk_bf16_f32 v137, v4, v5
	global_store_dwordx4 v157, v[134:137], s[18:19] offset:256
	s_branch .LBB0_186
